# weight-conversion phase: nt (streaming, L1-bypass) hint on the read-once f32 weight / input loads
# speedup vs baseline: 1.0325x; 1.0325x over previous
.LBB0_699:
	s_cmpk_gt_i32 s51, 0x57f
	s_mov_b64 s[6:7], -1
	s_cbranch_scc0 .LBB0_809
	s_cmpk_gt_u32 s51, 0xaff
	s_cbranch_scc0 .LBB0_794
	s_cmpk_gt_u32 s51, 0x107f
	s_cbranch_scc0 .LBB0_791
	s_cmpk_gt_u32 s51, 0x15ff
	s_cbranch_scc0 .LBB0_776
	s_cmpk_gt_u32 s51, 0x1b7f
	s_cbranch_scc0 .LBB0_761
	s_cmpk_gt_u32 s51, 0x20ff
	s_cbranch_scc0 .LBB0_758
	s_cmpk_gt_u32 s51, 0x27ff
	s_cbranch_scc0 .LBB0_743
	s_cmpk_gt_u32 s51, 0x29ff
	s_cbranch_scc0 .LBB0_740
	s_cmpk_gt_u32 s51, 0x2bff
	s_cbranch_scc0 .LBB0_725
	s_cmpk_gt_u32 s51, 0x2dff
	s_cbranch_scc0 .LBB0_722
	s_add_i32 s18, s51, 0xffffd200
	s_bfe_u32 s36, s18, 0x10009
	v_readlane_b32 s0, v250, 3
	s_lshl_b32 s6, s36, 3
	v_readlane_b32 s1, v250, 4
	s_load_dwordx2 s[6:7], s[0:1], s6 offset:0x80
	s_and_b32 s90, s18, 0xfffffc00
	s_lshl_b64 s[18:19], s[90:91], 12
	v_readlane_b32 s68, v250, 48
	v_readlane_b32 s80, v250, 60
	s_waitcnt lgkmcnt(0)
	s_add_u32 s26, s6, s18
	s_addc_u32 s27, s7, s19
	s_lshl_b64 s[6:7], s[90:91], 2
	v_readlane_b32 s81, v250, 61
	s_add_u32 s18, s80, s6
	s_addc_u32 s19, s81, s7
	s_add_i32 s6, s49, 0x5c00
	s_and_b32 s37, s6, 0x3c0
	s_lshl_b32 s6, s51, 5
	s_and_b32 s52, s6, 0x3e0
	s_lshl_b32 s6, s52, 2
	s_add_u32 s6, s26, s6
	v_or_b32_e32 v36, s37, v0
	s_addc_u32 s7, s27, 0
	v_mov_b32_e32 v79, v181
	v_lshl_add_u64 v[4:5], s[6:7], 0, v[78:79]
	v_lshlrev_b32_e32 v180, 12, v36
	v_lshl_add_u64 v[4:5], v[4:5], 0, v[180:181]
	s_mov_b32 s6, 0x8000
	v_add_co_u32_e32 v6, vcc, s6, v4
	s_mov_b32 s0, 0x10000
	s_nop 0
	v_addc_co_u32_e32 v7, vcc, 0, v5, vcc
	global_load_dwordx4 v[28:31], v[4:5], off nt
	global_load_dwordx4 v[32:35], v[6:7], off nt
	v_add_co_u32_e32 v6, vcc, s0, v4
	s_mov_b32 s0, 0x18000
	s_nop 0
	v_addc_co_u32_e32 v7, vcc, 0, v5, vcc
	v_add_co_u32_e32 v8, vcc, s0, v4
	s_mov_b32 s6, 0x20000
	s_nop 0
	v_addc_co_u32_e32 v9, vcc, 0, v5, vcc
	global_load_dwordx4 v[20:23], v[6:7], off nt
	global_load_dwordx4 v[24:27], v[8:9], off nt
	v_add_co_u32_e32 v6, vcc, s6, v4
	v_readlane_b32 s0, v250, 46
	s_nop 0
	v_addc_co_u32_e32 v7, vcc, 0, v5, vcc
	v_add_co_u32_e32 v8, vcc, 0x28000, v4
	v_readlane_b32 s1, v250, 47
	s_nop 0
	v_addc_co_u32_e32 v9, vcc, 0, v5, vcc
	global_load_dwordx4 v[12:15], v[6:7], off nt
	global_load_dwordx4 v[16:19], v[8:9], off nt
	v_add_co_u32_e32 v6, vcc, 0x30000, v4
	v_cndmask_b32_e64 v37, 0, 1, s[0:1]
	s_nop 0
	v_addc_co_u32_e32 v7, vcc, 0, v5, vcc
	v_add_co_u32_e32 v8, vcc, 0x38000, v4
	v_cmp_ne_u32_e64 s[6:7], 1, v37
	s_nop 0
	v_addc_co_u32_e32 v9, vcc, 0, v5, vcc
	global_load_dwordx4 v[4:7], v[6:7], off nt
	s_nop 0
	global_load_dwordx4 v[8:11], v[8:9], off nt
	s_andn2_b64 vcc, exec, s[0:1]
	v_add_lshl_u32 v79, s37, v0, 2
	v_readlane_b32 s69, v250, 49
	v_readlane_b32 s70, v250, 50
	v_readlane_b32 s71, v250, 51
	v_readlane_b32 s72, v250, 52
	v_readlane_b32 s73, v250, 53
	v_readlane_b32 s74, v250, 54
	v_readlane_b32 s75, v250, 55
	v_readlane_b32 s76, v250, 56
	v_readlane_b32 s77, v250, 57
	v_readlane_b32 s78, v250, 58
	v_readlane_b32 s79, v250, 59
	v_readlane_b32 s82, v250, 62
	v_readlane_b32 s83, v250, 63
	s_cbranch_vccnz .LBB0_846
	v_lshlrev_b32_e32 v36, 2, v36
	global_load_dword v36, v36, s[18:19] nt
	s_nop 0
	global_load_dword v92, v79, s[18:19] offset:32 nt
	s_waitcnt vmcnt(0)
	v_pk_mul_f32 v[80:81], v[30:31], v[36:37] op_sel_hi:[1,0]
	v_pk_mul_f32 v[82:83], v[28:29], v[36:37] op_sel_hi:[1,0]
	v_pk_mul_f32 v[38:39], v[34:35], v[92:93] op_sel_hi:[1,0]
	v_pk_mul_f32 v[36:37], v[32:33], v[92:93] op_sel_hi:[1,0]
	s_movk_i32 s1, 0xb1
	s_cbranch_execnz .LBB0_712

.LBB0_712:
	s_waitcnt vmcnt(0)
	v_add_u32_e32 v28, v3, v84
	ds_write2_b32 v28, v82, v83 offset1:1
	ds_write2_b32 v28, v80, v81 offset0:2 offset1:3
	v_add_u32_e32 v29, 0x420, v28
	v_add_u32_e32 v28, 0x428, v28
	s_and_b64 vcc, exec, s[6:7]
	ds_write2_b32 v29, v36, v37 offset1:1
	ds_write2_b32 v28, v38, v39 offset1:1
	s_cbranch_vccnz .LBB0_847
	global_load_dword v28, v79, s[18:19] offset:64 nt
	global_load_dword v36, v79, s[18:19] offset:96 nt
	s_waitcnt vmcnt(1)
	v_pk_mul_f32 v[32:33], v[22:23], v[28:29] op_sel_hi:[1,0]
	v_pk_mul_f32 v[34:35], v[20:21], v[28:29] op_sel_hi:[1,0]
	s_waitcnt vmcnt(0)
	v_pk_mul_f32 v[30:31], v[26:27], v[36:37] op_sel_hi:[1,0]
	v_pk_mul_f32 v[28:29], v[24:25], v[36:37] op_sel_hi:[1,0]
	s_cbranch_execnz .LBB0_715

.LBB0_715:
	v_add_u32_e32 v20, v3, v87
	ds_write2_b32 v20, v34, v35 offset1:1
	ds_write2_b32 v20, v32, v33 offset0:2 offset1:3
	v_add_u32_e32 v21, 0x420, v20
	v_add_u32_e32 v20, 0x428, v20
	s_and_b64 vcc, exec, s[6:7]
	ds_write2_b32 v21, v28, v29 offset1:1
	ds_write2_b32 v20, v30, v31 offset1:1
	s_cbranch_vccnz .LBB0_848
	global_load_dword v20, v79, s[18:19] offset:128 nt
	global_load_dword v28, v79, s[18:19] offset:160 nt
	s_waitcnt vmcnt(1)
	v_pk_mul_f32 v[24:25], v[14:15], v[20:21] op_sel_hi:[1,0]
	v_pk_mul_f32 v[26:27], v[12:13], v[20:21] op_sel_hi:[1,0]
	s_waitcnt vmcnt(0)
	v_pk_mul_f32 v[22:23], v[18:19], v[28:29] op_sel_hi:[1,0]
	v_pk_mul_f32 v[20:21], v[16:17], v[28:29] op_sel_hi:[1,0]
	s_cbranch_execnz .LBB0_718

.LBB0_718:
	v_add_u32_e32 v28, v3, v89
	v_add_u32_e32 v12, 0x420, v28
	ds_write2_b32 v12, v26, v27 offset1:1
	v_add_u32_e32 v12, 0x428, v28
	ds_write2_b32 v12, v24, v25 offset1:1
	v_add_u32_e32 v12, 0x840, v28
	ds_write2_b32 v12, v20, v21 offset1:1
	v_add_u32_e32 v12, 0x848, v28
	s_and_b64 vcc, exec, s[6:7]
	ds_write2_b32 v12, v22, v23 offset1:1
	s_cbranch_vccnz .LBB0_849
	global_load_dword v12, v79, s[18:19] offset:192 nt
	global_load_dword v20, v79, s[18:19] offset:224 nt
	s_waitcnt vmcnt(1)
	v_pk_mul_f32 v[16:17], v[6:7], v[12:13] op_sel_hi:[1,0]
	v_pk_mul_f32 v[18:19], v[4:5], v[12:13] op_sel_hi:[1,0]
	s_waitcnt vmcnt(0)
	v_pk_mul_f32 v[14:15], v[10:11], v[20:21] op_sel_hi:[1,0]
	v_pk_mul_f32 v[12:13], v[8:9], v[20:21] op_sel_hi:[1,0]
	s_cbranch_execnz .LBB0_721

.LBB0_722:
	s_and_b64 vcc, exec, s[6:7]
	s_cbranch_vccz .LBB0_724
	s_add_i32 s6, s49, 0x20400
	s_and_b32 s7, s6, 0x1ffc0
	s_lshl_b32 s6, s51, 5
	s_and_b32 s6, s6, 0x3e0
	v_or_b32_e32 v6, s7, v0
	s_lshl_b32 s90, s6, 2
	v_lshl_add_u64 v[4:5], v[58:59], 0, s[90:91]
	v_lshlrev_b32_e32 v180, 12, v6
	v_lshl_add_u64 v[32:33], v[4:5], 0, v[180:181]
	v_add_co_u32_e32 v8, vcc, 0x8000, v32
	global_load_dwordx4 v[4:7], v[32:33], off nt
	s_nop 0
	v_addc_co_u32_e32 v9, vcc, 0, v33, vcc
	s_mov_b32 s0, 0x10000
	global_load_dwordx4 v[8:11], v[8:9], off nt
	v_add_co_u32_e32 v12, vcc, s0, v32
	s_mov_b32 s0, 0x18000
	s_nop 0
	v_addc_co_u32_e32 v13, vcc, 0, v33, vcc
	global_load_dwordx4 v[12:15], v[12:13], off nt
	s_waitcnt vmcnt(0)
	v_add_co_u32_e32 v16, vcc, s0, v32
	v_add_u32_e32 v36, v3, v84
	s_nop 0
	v_addc_co_u32_e32 v17, vcc, 0, v33, vcc
	global_load_dwordx4 v[16:19], v[16:17], off nt
	v_add_co_u32_e32 v20, vcc, 0x20000, v32
	s_lshl_b32 s90, s7, 1
	s_nop 0
	v_addc_co_u32_e32 v21, vcc, 0, v33, vcc
	global_load_dwordx4 v[20:23], v[20:21], off nt
	v_add_co_u32_e32 v24, vcc, 0x28000, v32
	s_nop 1
	v_addc_co_u32_e32 v25, vcc, 0, v33, vcc
	global_load_dwordx4 v[24:27], v[24:25], off nt
	v_add_co_u32_e32 v28, vcc, 0x30000, v32
	s_nop 1
	v_addc_co_u32_e32 v29, vcc, 0, v33, vcc
	global_load_dwordx4 v[28:31], v[28:29], off nt
	v_add_co_u32_e32 v32, vcc, 0x38000, v32
	s_nop 1
	v_addc_co_u32_e32 v33, vcc, 0, v33, vcc
	global_load_dwordx4 v[32:35], v[32:33], off nt
	ds_write2_b32 v36, v4, v5 offset1:1
	ds_write2_b32 v36, v6, v7 offset0:2 offset1:3
	v_add_u32_e32 v4, 0x420, v36
	ds_write2_b32 v4, v8, v9 offset1:1
	v_add_u32_e32 v4, 0x428, v36
	ds_write2_b32 v4, v10, v11 offset1:1
	v_add_u32_e32 v4, 0x840, v36
	ds_write2_b32 v4, v12, v13 offset1:1
	v_add_u32_e32 v4, 0x848, v36
	ds_write2_b32 v4, v14, v15 offset1:1
	v_add_u32_e32 v4, 0xc60, v36
	s_waitcnt vmcnt(4)
	ds_write2_b32 v4, v16, v17 offset1:1
	v_add_u32_e32 v4, 0xc68, v36
	ds_write2_b32 v4, v18, v19 offset1:1
	v_add_u32_e32 v4, 0x1080, v36
	s_waitcnt vmcnt(3)
	ds_write2_b32 v4, v20, v21 offset1:1
	v_add_u32_e32 v4, 0x1088, v36
	ds_write2_b32 v4, v22, v23 offset1:1
	v_add_u32_e32 v4, 0x14a0, v36
	s_waitcnt vmcnt(2)
	ds_write2_b32 v4, v24, v25 offset1:1
	v_add_u32_e32 v4, 0x14a8, v36
	ds_write2_b32 v4, v26, v27 offset1:1
	v_add_u32_e32 v4, 0x18c0, v36
	s_waitcnt vmcnt(1)
	ds_write2_b32 v4, v28, v29 offset1:1
	v_add_u32_e32 v4, 0x18c8, v36
	ds_write2_b32 v4, v30, v31 offset1:1
	v_add_u32_e32 v4, 0x1ce0, v36
	s_waitcnt vmcnt(0)
	ds_write2_b32 v4, v32, v33 offset1:1
	v_add_u32_e32 v4, 0x1ce8, v36
	ds_write2_b32 v4, v34, v35 offset1:1
	s_waitcnt lgkmcnt(0)
	ds_read2_b32 v[10:11], v90 offset0:33 offset1:41
	ds_read2_b32 v[12:13], v90 offset1:8
	ds_read2_b32 v[14:15], v90 offset0:66 offset1:74
	ds_read2_b32 v[16:17], v90 offset0:99 offset1:107
	ds_read2_b32 v[18:19], v90 offset0:132 offset1:140
	ds_read2_b32 v[20:21], v90 offset0:165 offset1:173
	ds_read2_b32 v[22:23], v90 offset0:198 offset1:206
	ds_read2_b32 v[24:25], v90 offset0:231 offset1:239
	v_lshl_add_u64 v[4:5], v[42:43], 0, s[90:91]
	s_waitcnt lgkmcnt(6)
	v_cvt_pk_bf16_f32 v6, v12, v10
	v_or_b32_e32 v10, s6, v0
	v_lshlrev_b32_e32 v180, 11, v10
	v_or_b32_e32 v10, s6, v85
	s_waitcnt lgkmcnt(4)
	v_cvt_pk_bf16_f32 v7, v14, v16
	s_waitcnt lgkmcnt(2)
	v_cvt_pk_bf16_f32 v8, v18, v20
	s_waitcnt lgkmcnt(0)
	v_cvt_pk_bf16_f32 v9, v22, v24
	v_lshl_add_u64 v[26:27], v[4:5], 0, v[180:181]
	v_lshlrev_b32_e32 v180, 11, v10
	global_store_dwordx4 v[26:27], v[6:9], off
	s_nop 1
	v_cvt_pk_bf16_f32 v6, v13, v11
	v_cvt_pk_bf16_f32 v7, v15, v17
	v_cvt_pk_bf16_f32 v8, v19, v21
	v_cvt_pk_bf16_f32 v9, v23, v25
	v_lshl_add_u64 v[10:11], v[4:5], 0, v[180:181]
	global_store_dwordx4 v[10:11], v[6:9], off
	ds_read2_b32 v[10:11], v90 offset0:49 offset1:57
	ds_read2_b32 v[12:13], v90 offset0:16 offset1:24
	ds_read2_b32 v[14:15], v90 offset0:82 offset1:90
	ds_read2_b32 v[16:17], v90 offset0:115 offset1:123
	ds_read2_b32 v[18:19], v90 offset0:148 offset1:156
	ds_read2_b32 v[20:21], v90 offset0:181 offset1:189
	ds_read2_b32 v[22:23], v90 offset0:214 offset1:222
	ds_read2_b32 v[24:25], v90 offset0:247 offset1:255
	s_waitcnt lgkmcnt(6)
	v_cvt_pk_bf16_f32 v6, v12, v10
	v_or_b32_e32 v10, s6, v86
	v_lshlrev_b32_e32 v180, 11, v10
	v_or_b32_e32 v10, s6, v88
	s_waitcnt lgkmcnt(4)
	v_cvt_pk_bf16_f32 v7, v14, v16
	s_waitcnt lgkmcnt(2)
	v_cvt_pk_bf16_f32 v8, v18, v20
	s_waitcnt lgkmcnt(0)
	v_cvt_pk_bf16_f32 v9, v22, v24
	v_lshl_add_u64 v[26:27], v[4:5], 0, v[180:181]
	v_lshlrev_b32_e32 v180, 11, v10
	global_store_dwordx4 v[26:27], v[6:9], off
	v_lshl_add_u64 v[4:5], v[4:5], 0, v[180:181]
	s_nop 0
	v_cvt_pk_bf16_f32 v6, v13, v11
	v_cvt_pk_bf16_f32 v7, v15, v17
	v_cvt_pk_bf16_f32 v8, v19, v21
	v_cvt_pk_bf16_f32 v9, v23, v25
	global_store_dwordx4 v[4:5], v[6:9], off
	s_waitcnt lgkmcnt(0)

.LBB0_725:
	s_andn2_b64 vcc, exec, s[6:7]
	s_cbranch_vccnz .LBB0_739
	s_add_i32 s6, s49, 0x20800
	s_and_b32 s26, s6, 0x1ffc0
	s_lshl_b32 s6, s51, 5
	s_and_b32 s27, s6, 0x3e0
	v_or_b32_e32 v36, s26, v0
	s_lshl_b32 s90, s27, 2
	v_lshl_add_u64 v[4:5], v[60:61], 0, s[90:91]
	v_lshlrev_b32_e32 v180, 12, v36
	v_lshl_add_u64 v[4:5], v[4:5], 0, v[180:181]
	v_add_co_u32_e32 v6, vcc, 0x8000, v4
	s_mov_b32 s0, 0x10000
	s_nop 0
	v_addc_co_u32_e32 v7, vcc, 0, v5, vcc
	global_load_dwordx4 v[28:31], v[4:5], off nt
	global_load_dwordx4 v[32:35], v[6:7], off nt
	v_add_co_u32_e32 v6, vcc, s0, v4
	s_mov_b32 s0, 0x18000
	s_nop 0
	v_addc_co_u32_e32 v7, vcc, 0, v5, vcc
	v_add_co_u32_e32 v8, vcc, s0, v4
	v_readlane_b32 s18, v251, 0
	s_nop 0
	v_addc_co_u32_e32 v9, vcc, 0, v5, vcc
	global_load_dwordx4 v[20:23], v[6:7], off nt
	global_load_dwordx4 v[24:27], v[8:9], off nt
	v_add_co_u32_e32 v6, vcc, 0x20000, v4
	v_readlane_b32 s19, v251, 1
	s_nop 0
	v_addc_co_u32_e32 v7, vcc, 0, v5, vcc
	v_add_co_u32_e32 v8, vcc, 0x28000, v4
	v_cndmask_b32_e64 v37, 0, 1, s[18:19]
	s_nop 0
	v_addc_co_u32_e32 v9, vcc, 0, v5, vcc
	global_load_dwordx4 v[12:15], v[6:7], off nt
	global_load_dwordx4 v[16:19], v[8:9], off nt
	v_add_co_u32_e32 v6, vcc, 0x30000, v4
	v_cmp_ne_u32_e64 s[6:7], 1, v37
	s_nop 0
	v_addc_co_u32_e32 v7, vcc, 0, v5, vcc
	v_add_co_u32_e32 v8, vcc, 0x38000, v4
	v_add_lshl_u32 v79, s26, v0, 2
	s_nop 0
	v_addc_co_u32_e32 v9, vcc, 0, v5, vcc
	global_load_dwordx4 v[4:7], v[6:7], off nt
	s_nop 0
	global_load_dwordx4 v[8:11], v[8:9], off nt
	s_andn2_b64 vcc, exec, s[18:19]
	s_cbranch_vccnz .LBB0_842
	v_lshlrev_b32_e32 v36, 2, v36
	global_load_dword v36, v36, s[10:11] nt
	s_nop 0
	global_load_dword v92, v79, s[10:11] offset:32 nt
	s_waitcnt vmcnt(0)
	v_pk_mul_f32 v[80:81], v[30:31], v[36:37] op_sel_hi:[1,0]
	v_pk_mul_f32 v[82:83], v[28:29], v[36:37] op_sel_hi:[1,0]
	v_pk_mul_f32 v[38:39], v[34:35], v[92:93] op_sel_hi:[1,0]
	v_pk_mul_f32 v[36:37], v[32:33], v[92:93] op_sel_hi:[1,0]
	s_cbranch_execnz .LBB0_729

.LBB0_729:
	s_waitcnt vmcnt(0)
	v_add_u32_e32 v28, v3, v84
	ds_write2_b32 v28, v82, v83 offset1:1
	ds_write2_b32 v28, v80, v81 offset0:2 offset1:3
	v_add_u32_e32 v29, 0x420, v28
	v_add_u32_e32 v28, 0x428, v28
	s_and_b64 vcc, exec, s[6:7]
	ds_write2_b32 v29, v36, v37 offset1:1
	ds_write2_b32 v28, v38, v39 offset1:1
	s_cbranch_vccnz .LBB0_843
	global_load_dword v28, v79, s[10:11] offset:64 nt
	global_load_dword v36, v79, s[10:11] offset:96 nt
	s_waitcnt vmcnt(1)
	v_pk_mul_f32 v[32:33], v[22:23], v[28:29] op_sel_hi:[1,0]
	v_pk_mul_f32 v[34:35], v[20:21], v[28:29] op_sel_hi:[1,0]
	s_waitcnt vmcnt(0)
	v_pk_mul_f32 v[30:31], v[26:27], v[36:37] op_sel_hi:[1,0]
	v_pk_mul_f32 v[28:29], v[24:25], v[36:37] op_sel_hi:[1,0]
	s_cbranch_execnz .LBB0_732

.LBB0_732:
	v_add_u32_e32 v20, v3, v87
	ds_write2_b32 v20, v34, v35 offset1:1
	ds_write2_b32 v20, v32, v33 offset0:2 offset1:3
	v_add_u32_e32 v21, 0x420, v20
	v_add_u32_e32 v20, 0x428, v20
	s_and_b64 vcc, exec, s[6:7]
	ds_write2_b32 v21, v28, v29 offset1:1
	ds_write2_b32 v20, v30, v31 offset1:1
	s_cbranch_vccnz .LBB0_844
	global_load_dword v20, v79, s[10:11] offset:128 nt
	global_load_dword v28, v79, s[10:11] offset:160 nt
	s_waitcnt vmcnt(1)
	v_pk_mul_f32 v[24:25], v[14:15], v[20:21] op_sel_hi:[1,0]
	v_pk_mul_f32 v[26:27], v[12:13], v[20:21] op_sel_hi:[1,0]
	s_waitcnt vmcnt(0)
	v_pk_mul_f32 v[22:23], v[18:19], v[28:29] op_sel_hi:[1,0]
	v_pk_mul_f32 v[20:21], v[16:17], v[28:29] op_sel_hi:[1,0]
	s_cbranch_execnz .LBB0_735

.LBB0_735:
	v_add_u32_e32 v28, v3, v89
	v_add_u32_e32 v12, 0x420, v28
	ds_write2_b32 v12, v26, v27 offset1:1
	v_add_u32_e32 v12, 0x428, v28
	ds_write2_b32 v12, v24, v25 offset1:1
	v_add_u32_e32 v12, 0x840, v28
	ds_write2_b32 v12, v20, v21 offset1:1
	v_add_u32_e32 v12, 0x848, v28
	s_and_b64 vcc, exec, s[6:7]
	ds_write2_b32 v12, v22, v23 offset1:1
	s_cbranch_vccnz .LBB0_845
	global_load_dword v12, v79, s[10:11] offset:192 nt
	global_load_dword v20, v79, s[10:11] offset:224 nt
	s_waitcnt vmcnt(1)
	v_pk_mul_f32 v[16:17], v[6:7], v[12:13] op_sel_hi:[1,0]
	v_pk_mul_f32 v[18:19], v[4:5], v[12:13] op_sel_hi:[1,0]
	s_waitcnt vmcnt(0)
	v_pk_mul_f32 v[14:15], v[10:11], v[20:21] op_sel_hi:[1,0]
	v_pk_mul_f32 v[12:13], v[8:9], v[20:21] op_sel_hi:[1,0]
	s_cbranch_execnz .LBB0_738

.LBB0_740:
	s_andn2_b64 vcc, exec, s[6:7]
	s_cbranch_vccnz .LBB0_742
	s_add_i32 s6, s49, 0x20c00
	s_and_b32 s7, s6, 0x1ffc0
	s_lshl_b32 s6, s51, 5
	s_and_b32 s6, s6, 0x3e0
	v_or_b32_e32 v6, s7, v0
	s_lshl_b32 s90, s6, 2
	v_lshl_add_u64 v[4:5], v[62:63], 0, s[90:91]
	v_lshlrev_b32_e32 v180, 12, v6
	v_lshl_add_u64 v[32:33], v[4:5], 0, v[180:181]
	v_add_co_u32_e32 v8, vcc, 0x8000, v32
	global_load_dwordx4 v[4:7], v[32:33], off nt
	s_nop 0
	v_addc_co_u32_e32 v9, vcc, 0, v33, vcc
	s_mov_b32 s0, 0x10000
	global_load_dwordx4 v[8:11], v[8:9], off nt
	v_add_co_u32_e32 v12, vcc, s0, v32
	s_mov_b32 s0, 0x18000
	s_nop 0
	v_addc_co_u32_e32 v13, vcc, 0, v33, vcc
	global_load_dwordx4 v[12:15], v[12:13], off nt
	s_waitcnt vmcnt(0)
	v_add_co_u32_e32 v16, vcc, s0, v32
	v_add_u32_e32 v36, v3, v84
	s_nop 0
	v_addc_co_u32_e32 v17, vcc, 0, v33, vcc
	global_load_dwordx4 v[16:19], v[16:17], off nt
	v_add_co_u32_e32 v20, vcc, 0x20000, v32
	s_lshl_b32 s90, s7, 1
	s_nop 0
	v_addc_co_u32_e32 v21, vcc, 0, v33, vcc
	global_load_dwordx4 v[20:23], v[20:21], off nt
	v_add_co_u32_e32 v24, vcc, 0x28000, v32
	s_nop 1
	v_addc_co_u32_e32 v25, vcc, 0, v33, vcc
	global_load_dwordx4 v[24:27], v[24:25], off nt
	v_add_co_u32_e32 v28, vcc, 0x30000, v32
	s_nop 1
	v_addc_co_u32_e32 v29, vcc, 0, v33, vcc
	global_load_dwordx4 v[28:31], v[28:29], off nt
	v_add_co_u32_e32 v32, vcc, 0x38000, v32
	s_nop 1
	v_addc_co_u32_e32 v33, vcc, 0, v33, vcc
	global_load_dwordx4 v[32:35], v[32:33], off nt
	ds_write2_b32 v36, v4, v5 offset1:1
	ds_write2_b32 v36, v6, v7 offset0:2 offset1:3
	v_add_u32_e32 v4, 0x420, v36
	ds_write2_b32 v4, v8, v9 offset1:1
	v_add_u32_e32 v4, 0x428, v36
	ds_write2_b32 v4, v10, v11 offset1:1
	v_add_u32_e32 v4, 0x840, v36
	ds_write2_b32 v4, v12, v13 offset1:1
	v_add_u32_e32 v4, 0x848, v36
	ds_write2_b32 v4, v14, v15 offset1:1
	v_add_u32_e32 v4, 0xc60, v36
	s_waitcnt vmcnt(4)
	ds_write2_b32 v4, v16, v17 offset1:1
	v_add_u32_e32 v4, 0xc68, v36
	ds_write2_b32 v4, v18, v19 offset1:1
	v_add_u32_e32 v4, 0x1080, v36
	s_waitcnt vmcnt(3)
	ds_write2_b32 v4, v20, v21 offset1:1
	v_add_u32_e32 v4, 0x1088, v36
	ds_write2_b32 v4, v22, v23 offset1:1
	v_add_u32_e32 v4, 0x14a0, v36
	s_waitcnt vmcnt(2)
	ds_write2_b32 v4, v24, v25 offset1:1
	v_add_u32_e32 v4, 0x14a8, v36
	ds_write2_b32 v4, v26, v27 offset1:1
	v_add_u32_e32 v4, 0x18c0, v36
	s_waitcnt vmcnt(1)
	ds_write2_b32 v4, v28, v29 offset1:1
	v_add_u32_e32 v4, 0x18c8, v36
	ds_write2_b32 v4, v30, v31 offset1:1
	v_add_u32_e32 v4, 0x1ce0, v36
	s_waitcnt vmcnt(0)
	ds_write2_b32 v4, v32, v33 offset1:1
	v_add_u32_e32 v4, 0x1ce8, v36
	ds_write2_b32 v4, v34, v35 offset1:1
	s_waitcnt lgkmcnt(0)
	ds_read2_b32 v[10:11], v90 offset0:33 offset1:41
	ds_read2_b32 v[12:13], v90 offset1:8
	ds_read2_b32 v[14:15], v90 offset0:66 offset1:74
	ds_read2_b32 v[16:17], v90 offset0:99 offset1:107
	ds_read2_b32 v[18:19], v90 offset0:132 offset1:140
	ds_read2_b32 v[20:21], v90 offset0:165 offset1:173
	ds_read2_b32 v[22:23], v90 offset0:198 offset1:206
	ds_read2_b32 v[24:25], v90 offset0:231 offset1:239
	v_lshl_add_u64 v[4:5], v[46:47], 0, s[90:91]
	s_waitcnt lgkmcnt(6)
	v_cvt_pk_bf16_f32 v6, v12, v10
	v_or_b32_e32 v10, s6, v0
	v_lshlrev_b32_e32 v180, 11, v10
	v_or_b32_e32 v10, s6, v85
	s_waitcnt lgkmcnt(4)
	v_cvt_pk_bf16_f32 v7, v14, v16
	s_waitcnt lgkmcnt(2)
	v_cvt_pk_bf16_f32 v8, v18, v20
	s_waitcnt lgkmcnt(0)
	v_cvt_pk_bf16_f32 v9, v22, v24
	v_lshl_add_u64 v[26:27], v[4:5], 0, v[180:181]
	v_lshlrev_b32_e32 v180, 11, v10
	global_store_dwordx4 v[26:27], v[6:9], off
	s_nop 1
	v_cvt_pk_bf16_f32 v6, v13, v11
	v_cvt_pk_bf16_f32 v7, v15, v17
	v_cvt_pk_bf16_f32 v8, v19, v21
	v_cvt_pk_bf16_f32 v9, v23, v25
	v_lshl_add_u64 v[10:11], v[4:5], 0, v[180:181]
	global_store_dwordx4 v[10:11], v[6:9], off
	ds_read2_b32 v[10:11], v90 offset0:49 offset1:57
	ds_read2_b32 v[12:13], v90 offset0:16 offset1:24
	ds_read2_b32 v[14:15], v90 offset0:82 offset1:90
	ds_read2_b32 v[16:17], v90 offset0:115 offset1:123
	ds_read2_b32 v[18:19], v90 offset0:148 offset1:156
	ds_read2_b32 v[20:21], v90 offset0:181 offset1:189
	ds_read2_b32 v[22:23], v90 offset0:214 offset1:222
	ds_read2_b32 v[24:25], v90 offset0:247 offset1:255
	s_waitcnt lgkmcnt(6)
	v_cvt_pk_bf16_f32 v6, v12, v10
	v_or_b32_e32 v10, s6, v86
	v_lshlrev_b32_e32 v180, 11, v10
	v_or_b32_e32 v10, s6, v88
	s_waitcnt lgkmcnt(4)
	v_cvt_pk_bf16_f32 v7, v14, v16
	s_waitcnt lgkmcnt(2)
	v_cvt_pk_bf16_f32 v8, v18, v20
	s_waitcnt lgkmcnt(0)
	v_cvt_pk_bf16_f32 v9, v22, v24
	v_lshl_add_u64 v[26:27], v[4:5], 0, v[180:181]
	v_lshlrev_b32_e32 v180, 11, v10
	global_store_dwordx4 v[26:27], v[6:9], off
	v_lshl_add_u64 v[4:5], v[4:5], 0, v[180:181]
	s_nop 0
	v_cvt_pk_bf16_f32 v6, v13, v11
	v_cvt_pk_bf16_f32 v7, v15, v17
	v_cvt_pk_bf16_f32 v8, v19, v21
	v_cvt_pk_bf16_f32 v9, v23, v25
	global_store_dwordx4 v[4:5], v[6:9], off
	s_waitcnt lgkmcnt(0)

.LBB0_743:
	s_andn2_b64 vcc, exec, s[6:7]
	s_cbranch_vccnz .LBB0_757
	s_add_i32 s6, s51, 0xdf00
	s_bfe_u32 s7, s6, 0xc0004
	s_mulk_i32 s7, 0x2493
	s_lshr_b32 s7, s7, 16
	s_mul_i32 s18, s7, 0x70
	s_sub_i32 s27, s6, s18
	s_lshl_b32 s6, s27, 7
	s_lshl_b32 s26, s7, 6
	s_and_b32 s90, s6, 0x3ff80
	v_or_b32_e32 v36, s26, v0
	v_lshl_add_u64 v[4:5], v[64:65], 0, s[90:91]
	s_movk_i32 s6, 0x3820
	v_mad_u64_u32 v[6:7], s[6:7], v36, s6, v[4:5]
	v_mul_u32_u24_e32 v180, 0x3820, v36
	v_lshl_add_u64 v[4:5], v[4:5], 0, v[180:181]
	s_mov_b32 s6, 0x1c000
	v_add_co_u32_e32 v8, vcc, s6, v4
	s_mov_b32 s6, 0x38000
	s_nop 0
	v_addc_co_u32_e32 v9, vcc, 0, v5, vcc
	global_load_dwordx4 v[28:31], v[6:7], off nt
	global_load_dwordx4 v[32:35], v[8:9], off offset:256 nt
	v_add_co_u32_e32 v6, vcc, s6, v4
	s_mov_b32 s6, 0x54000
	s_nop 0
	v_addc_co_u32_e32 v7, vcc, 0, v5, vcc
	v_add_co_u32_e32 v8, vcc, s6, v4
	s_mov_b32 s6, 0x70000
	s_nop 0
	v_addc_co_u32_e32 v9, vcc, 0, v5, vcc
	global_load_dwordx4 v[20:23], v[6:7], off offset:512 nt
	global_load_dwordx4 v[24:27], v[8:9], off offset:768 nt
	v_add_co_u32_e32 v6, vcc, s6, v4
	v_readlane_b32 s18, v251, 2
	s_nop 0
	v_addc_co_u32_e32 v7, vcc, 0, v5, vcc
	v_add_co_u32_e32 v8, vcc, 0x8c000, v4
	v_readlane_b32 s19, v251, 3
	s_nop 0
	v_addc_co_u32_e32 v9, vcc, 0, v5, vcc
	global_load_dwordx4 v[12:15], v[6:7], off offset:1024 nt
	global_load_dwordx4 v[16:19], v[8:9], off offset:1280 nt
	v_add_co_u32_e32 v6, vcc, 0xa8000, v4
	v_cndmask_b32_e64 v37, 0, 1, s[18:19]
	s_nop 0
	v_addc_co_u32_e32 v7, vcc, 0, v5, vcc
	v_add_co_u32_e32 v8, vcc, 0xc4000, v4
	v_cmp_ne_u32_e64 s[6:7], 1, v37
	s_nop 0
	v_addc_co_u32_e32 v9, vcc, 0, v5, vcc
	global_load_dwordx4 v[4:7], v[6:7], off offset:1536 nt
	s_nop 0
	global_load_dwordx4 v[8:11], v[8:9], off offset:1792 nt
	s_andn2_b64 vcc, exec, s[18:19]
	v_add_lshl_u32 v79, v0, s26, 2
	s_cbranch_vccnz .LBB0_838
	v_lshlrev_b32_e32 v36, 2, v36
	global_load_dword v36, v36, s[12:13] nt
	s_nop 0
	global_load_dword v92, v79, s[12:13] offset:32 nt
	s_waitcnt vmcnt(0)
	v_pk_mul_f32 v[80:81], v[30:31], v[36:37] op_sel_hi:[1,0]
	v_pk_mul_f32 v[82:83], v[28:29], v[36:37] op_sel_hi:[1,0]
	v_pk_mul_f32 v[38:39], v[34:35], v[92:93] op_sel_hi:[1,0]
	v_pk_mul_f32 v[36:37], v[32:33], v[92:93] op_sel_hi:[1,0]
	s_cbranch_execnz .LBB0_747

.LBB0_747:
	s_waitcnt vmcnt(0)
	v_add_u32_e32 v28, v3, v84
	ds_write2_b32 v28, v82, v83 offset1:1
	ds_write2_b32 v28, v80, v81 offset0:2 offset1:3
	v_add_u32_e32 v29, 0x420, v28
	v_add_u32_e32 v28, 0x428, v28
	s_and_b64 vcc, exec, s[6:7]
	ds_write2_b32 v29, v36, v37 offset1:1
	ds_write2_b32 v28, v38, v39 offset1:1
	s_cbranch_vccnz .LBB0_839
	global_load_dword v28, v79, s[12:13] offset:64 nt
	global_load_dword v36, v79, s[12:13] offset:96 nt
	s_waitcnt vmcnt(1)
	v_pk_mul_f32 v[32:33], v[22:23], v[28:29] op_sel_hi:[1,0]
	v_pk_mul_f32 v[34:35], v[20:21], v[28:29] op_sel_hi:[1,0]
	s_waitcnt vmcnt(0)
	v_pk_mul_f32 v[30:31], v[26:27], v[36:37] op_sel_hi:[1,0]
	v_pk_mul_f32 v[28:29], v[24:25], v[36:37] op_sel_hi:[1,0]
	s_cbranch_execnz .LBB0_750

.LBB0_750:
	v_add_u32_e32 v20, v3, v87
	ds_write2_b32 v20, v34, v35 offset1:1
	ds_write2_b32 v20, v32, v33 offset0:2 offset1:3
	v_add_u32_e32 v21, 0x420, v20
	v_add_u32_e32 v20, 0x428, v20
	s_and_b64 vcc, exec, s[6:7]
	ds_write2_b32 v21, v28, v29 offset1:1
	ds_write2_b32 v20, v30, v31 offset1:1
	s_cbranch_vccnz .LBB0_840
	global_load_dword v20, v79, s[12:13] offset:128 nt
	global_load_dword v28, v79, s[12:13] offset:160 nt
	s_waitcnt vmcnt(1)
	v_pk_mul_f32 v[24:25], v[14:15], v[20:21] op_sel_hi:[1,0]
	v_pk_mul_f32 v[26:27], v[12:13], v[20:21] op_sel_hi:[1,0]
	s_waitcnt vmcnt(0)
	v_pk_mul_f32 v[22:23], v[18:19], v[28:29] op_sel_hi:[1,0]
	v_pk_mul_f32 v[20:21], v[16:17], v[28:29] op_sel_hi:[1,0]
	s_cbranch_execnz .LBB0_753

.LBB0_753:
	v_add_u32_e32 v28, v3, v89
	v_add_u32_e32 v12, 0x420, v28
	ds_write2_b32 v12, v26, v27 offset1:1
	v_add_u32_e32 v12, 0x428, v28
	ds_write2_b32 v12, v24, v25 offset1:1
	v_add_u32_e32 v12, 0x840, v28
	ds_write2_b32 v12, v20, v21 offset1:1
	v_add_u32_e32 v12, 0x848, v28
	s_and_b64 vcc, exec, s[6:7]
	ds_write2_b32 v12, v22, v23 offset1:1
	s_cbranch_vccnz .LBB0_841
	global_load_dword v12, v79, s[12:13] offset:192 nt
	global_load_dword v20, v79, s[12:13] offset:224 nt
	s_waitcnt vmcnt(1)
	v_pk_mul_f32 v[16:17], v[6:7], v[12:13] op_sel_hi:[1,0]
	v_pk_mul_f32 v[18:19], v[4:5], v[12:13] op_sel_hi:[1,0]
	s_waitcnt vmcnt(0)
	v_pk_mul_f32 v[14:15], v[10:11], v[20:21] op_sel_hi:[1,0]
	v_pk_mul_f32 v[12:13], v[8:9], v[20:21] op_sel_hi:[1,0]
	s_cbranch_execnz .LBB0_756

.LBB0_758:
	s_andn2_b64 vcc, exec, s[6:7]
	s_cbranch_vccnz .LBB0_760
	s_add_i32 s6, s49, 0x22500
	s_and_b32 s7, s6, 0x1ffc0
	s_lshl_b32 s6, s51, 5
	s_and_b32 s6, s6, 0x3e0
	v_or_b32_e32 v6, s7, v0
	s_lshl_b32 s90, s6, 2
	v_lshl_add_u64 v[4:5], v[66:67], 0, s[90:91]
	v_lshlrev_b32_e32 v180, 12, v6
	v_lshl_add_u64 v[32:33], v[4:5], 0, v[180:181]
	v_add_co_u32_e32 v8, vcc, 0x8000, v32
	global_load_dwordx4 v[4:7], v[32:33], off nt
	s_nop 0
	v_addc_co_u32_e32 v9, vcc, 0, v33, vcc
	s_mov_b32 s0, 0x10000
	global_load_dwordx4 v[8:11], v[8:9], off nt
	v_add_co_u32_e32 v12, vcc, s0, v32
	s_mov_b32 s0, 0x18000
	s_nop 0
	v_addc_co_u32_e32 v13, vcc, 0, v33, vcc
	global_load_dwordx4 v[12:15], v[12:13], off nt
	s_waitcnt vmcnt(0)
	v_add_co_u32_e32 v16, vcc, s0, v32
	v_add_u32_e32 v36, v3, v84
	s_nop 0
	v_addc_co_u32_e32 v17, vcc, 0, v33, vcc
	global_load_dwordx4 v[16:19], v[16:17], off nt
	v_add_co_u32_e32 v20, vcc, 0x20000, v32
	s_lshl_b32 s90, s7, 1
	s_nop 0
	v_addc_co_u32_e32 v21, vcc, 0, v33, vcc
	global_load_dwordx4 v[20:23], v[20:21], off nt
	v_add_co_u32_e32 v24, vcc, 0x28000, v32
	s_nop 1
	v_addc_co_u32_e32 v25, vcc, 0, v33, vcc
	global_load_dwordx4 v[24:27], v[24:25], off nt
	v_add_co_u32_e32 v28, vcc, 0x30000, v32
	s_nop 1
	v_addc_co_u32_e32 v29, vcc, 0, v33, vcc
	global_load_dwordx4 v[28:31], v[28:29], off nt
	v_add_co_u32_e32 v32, vcc, 0x38000, v32
	s_nop 1
	v_addc_co_u32_e32 v33, vcc, 0, v33, vcc
	global_load_dwordx4 v[32:35], v[32:33], off nt
	ds_write2_b32 v36, v4, v5 offset1:1
	ds_write2_b32 v36, v6, v7 offset0:2 offset1:3
	v_add_u32_e32 v4, 0x420, v36
	ds_write2_b32 v4, v8, v9 offset1:1
	v_add_u32_e32 v4, 0x428, v36
	ds_write2_b32 v4, v10, v11 offset1:1
	v_add_u32_e32 v4, 0x840, v36
	ds_write2_b32 v4, v12, v13 offset1:1
	v_add_u32_e32 v4, 0x848, v36
	ds_write2_b32 v4, v14, v15 offset1:1
	v_add_u32_e32 v4, 0xc60, v36
	s_waitcnt vmcnt(4)
	ds_write2_b32 v4, v16, v17 offset1:1
	v_add_u32_e32 v4, 0xc68, v36
	ds_write2_b32 v4, v18, v19 offset1:1
	v_add_u32_e32 v4, 0x1080, v36
	s_waitcnt vmcnt(3)
	ds_write2_b32 v4, v20, v21 offset1:1
	v_add_u32_e32 v4, 0x1088, v36
	ds_write2_b32 v4, v22, v23 offset1:1
	v_add_u32_e32 v4, 0x14a0, v36
	s_waitcnt vmcnt(2)
	ds_write2_b32 v4, v24, v25 offset1:1
	v_add_u32_e32 v4, 0x14a8, v36
	ds_write2_b32 v4, v26, v27 offset1:1
	v_add_u32_e32 v4, 0x18c0, v36
	s_waitcnt vmcnt(1)
	ds_write2_b32 v4, v28, v29 offset1:1
	v_add_u32_e32 v4, 0x18c8, v36
	ds_write2_b32 v4, v30, v31 offset1:1
	v_add_u32_e32 v4, 0x1ce0, v36
	s_waitcnt vmcnt(0)
	ds_write2_b32 v4, v32, v33 offset1:1
	v_add_u32_e32 v4, 0x1ce8, v36
	ds_write2_b32 v4, v34, v35 offset1:1
	s_waitcnt lgkmcnt(0)
	ds_read2_b32 v[10:11], v90 offset0:33 offset1:41
	ds_read2_b32 v[12:13], v90 offset1:8
	ds_read2_b32 v[14:15], v90 offset0:66 offset1:74
	ds_read2_b32 v[16:17], v90 offset0:99 offset1:107
	ds_read2_b32 v[18:19], v90 offset0:132 offset1:140
	ds_read2_b32 v[20:21], v90 offset0:165 offset1:173
	ds_read2_b32 v[22:23], v90 offset0:198 offset1:206
	ds_read2_b32 v[24:25], v90 offset0:231 offset1:239
	v_lshl_add_u64 v[4:5], v[50:51], 0, s[90:91]
	s_waitcnt lgkmcnt(6)
	v_cvt_pk_bf16_f32 v6, v12, v10
	v_or_b32_e32 v10, s6, v0
	v_mul_u32_u24_e32 v180, 0x1600, v10
	v_or_b32_e32 v10, s6, v85
	s_waitcnt lgkmcnt(4)
	v_cvt_pk_bf16_f32 v7, v14, v16
	s_waitcnt lgkmcnt(2)
	v_cvt_pk_bf16_f32 v8, v18, v20
	s_waitcnt lgkmcnt(0)
	v_cvt_pk_bf16_f32 v9, v22, v24
	v_lshl_add_u64 v[26:27], v[4:5], 0, v[180:181]
	v_mul_u32_u24_e32 v180, 0x1600, v10
	global_store_dwordx4 v[26:27], v[6:9], off
	s_nop 1
	v_cvt_pk_bf16_f32 v6, v13, v11
	v_cvt_pk_bf16_f32 v7, v15, v17
	v_cvt_pk_bf16_f32 v8, v19, v21
	v_cvt_pk_bf16_f32 v9, v23, v25
	v_lshl_add_u64 v[10:11], v[4:5], 0, v[180:181]
	global_store_dwordx4 v[10:11], v[6:9], off
	ds_read2_b32 v[10:11], v90 offset0:16 offset1:24
	ds_read2_b32 v[12:13], v90 offset0:49 offset1:57
	ds_read2_b32 v[14:15], v90 offset0:82 offset1:90
	ds_read2_b32 v[16:17], v90 offset0:115 offset1:123
	ds_read2_b32 v[18:19], v90 offset0:148 offset1:156
	ds_read2_b32 v[20:21], v90 offset0:181 offset1:189
	ds_read2_b32 v[22:23], v90 offset0:214 offset1:222
	ds_read2_b32 v[24:25], v90 offset0:247 offset1:255
	s_waitcnt lgkmcnt(6)
	v_cvt_pk_bf16_f32 v6, v10, v12
	v_or_b32_e32 v10, s6, v86
	v_mul_u32_u24_e32 v180, 0x1600, v10
	v_or_b32_e32 v10, s6, v88
	s_waitcnt lgkmcnt(4)
	v_cvt_pk_bf16_f32 v7, v14, v16
	s_waitcnt lgkmcnt(2)
	v_cvt_pk_bf16_f32 v8, v18, v20
	s_waitcnt lgkmcnt(0)
	v_cvt_pk_bf16_f32 v9, v22, v24
	v_lshl_add_u64 v[26:27], v[4:5], 0, v[180:181]
	v_mul_u32_u24_e32 v180, 0x1600, v10
	global_store_dwordx4 v[26:27], v[6:9], off
	v_lshl_add_u64 v[4:5], v[4:5], 0, v[180:181]
	s_nop 0
	v_cvt_pk_bf16_f32 v6, v11, v13
	v_cvt_pk_bf16_f32 v7, v15, v17
	v_cvt_pk_bf16_f32 v8, v19, v21
	v_cvt_pk_bf16_f32 v9, v23, v25
	global_store_dwordx4 v[4:5], v[6:9], off
	s_waitcnt lgkmcnt(0)

.LBB0_761:
	s_andn2_b64 vcc, exec, s[6:7]
	s_cbranch_vccnz .LBB0_775
	s_add_i32 s6, s51, 0xea00
	s_and_b32 s7, s6, 0xffff
	s_mul_i32 s7, s7, 0xba2f
	s_lshr_b32 s18, s7, 16
	s_lshr_b32 s7, s7, 22
	s_mulk_i32 s7, 0x58
	s_sub_i32 s6, s6, s7
	s_and_b32 s27, s6, 0xffff
	s_and_b32 s26, s18, 0xffc0
	v_or_b32_e32 v36, s26, v0
	s_lshl_b32 s90, s27, 7
	v_lshl_add_u64 v[4:5], v[68:69], 0, s[90:91]
	v_mul_u32_u24_e32 v180, 0x2c00, v36
	v_mad_u64_u32 v[6:7], s[6:7], v36, s66, v[4:5]
	v_lshl_add_u64 v[4:5], v[4:5], 0, v[180:181]
	s_mov_b32 s0, 0x16000
	v_add_co_u32_e32 v8, vcc, s0, v4
	s_mov_b32 s0, 0x2c000
	s_nop 0
	v_addc_co_u32_e32 v9, vcc, 0, v5, vcc
	global_load_dwordx4 v[28:31], v[6:7], off nt
	global_load_dwordx4 v[32:35], v[8:9], off nt
	v_add_co_u32_e32 v6, vcc, s0, v4
	s_mov_b32 s0, 0x42000
	s_nop 0
	v_addc_co_u32_e32 v7, vcc, 0, v5, vcc
	v_add_co_u32_e32 v8, vcc, s0, v4
	s_mov_b32 s0, 0x58000
	s_nop 0
	v_addc_co_u32_e32 v9, vcc, 0, v5, vcc
	global_load_dwordx4 v[20:23], v[6:7], off nt
	global_load_dwordx4 v[24:27], v[8:9], off nt
	v_add_co_u32_e32 v6, vcc, s0, v4
	v_readlane_b32 s18, v251, 20
	s_nop 0
	v_addc_co_u32_e32 v7, vcc, 0, v5, vcc
	v_add_co_u32_e32 v8, vcc, 0x6e000, v4
	v_readlane_b32 s19, v251, 21
	s_nop 0
	v_addc_co_u32_e32 v9, vcc, 0, v5, vcc
	global_load_dwordx4 v[12:15], v[6:7], off nt
	global_load_dwordx4 v[16:19], v[8:9], off nt
	v_add_co_u32_e32 v6, vcc, 0x84000, v4
	v_cndmask_b32_e64 v37, 0, 1, s[18:19]
	s_nop 0
	v_addc_co_u32_e32 v7, vcc, 0, v5, vcc
	v_add_co_u32_e32 v8, vcc, 0x9a000, v4
	v_cmp_ne_u32_e64 s[6:7], 1, v37
	s_nop 0
	v_addc_co_u32_e32 v9, vcc, 0, v5, vcc
	global_load_dwordx4 v[4:7], v[6:7], off nt
	s_nop 0
	global_load_dwordx4 v[8:11], v[8:9], off nt
	s_andn2_b64 vcc, exec, s[18:19]
	v_add_lshl_u32 v79, v0, s26, 2
	s_cbranch_vccnz .LBB0_834
	v_lshlrev_b32_e32 v36, 2, v36
	global_load_dword v36, v36, s[14:15] nt
	s_nop 0
	global_load_dword v92, v79, s[14:15] offset:32 nt
	s_waitcnt vmcnt(0)
	v_pk_mul_f32 v[80:81], v[30:31], v[36:37] op_sel_hi:[1,0]
	v_pk_mul_f32 v[82:83], v[28:29], v[36:37] op_sel_hi:[1,0]
	v_pk_mul_f32 v[38:39], v[34:35], v[92:93] op_sel_hi:[1,0]
	v_pk_mul_f32 v[36:37], v[32:33], v[92:93] op_sel_hi:[1,0]
	s_cbranch_execnz .LBB0_765

.LBB0_765:
	s_waitcnt vmcnt(0)
	v_add_u32_e32 v28, v3, v84
	ds_write2_b32 v28, v82, v83 offset1:1
	ds_write2_b32 v28, v80, v81 offset0:2 offset1:3
	v_add_u32_e32 v29, 0x420, v28
	v_add_u32_e32 v28, 0x428, v28
	s_and_b64 vcc, exec, s[6:7]
	ds_write2_b32 v29, v36, v37 offset1:1
	ds_write2_b32 v28, v38, v39 offset1:1
	s_cbranch_vccnz .LBB0_835
	global_load_dword v28, v79, s[14:15] offset:64 nt
	global_load_dword v36, v79, s[14:15] offset:96 nt
	s_waitcnt vmcnt(1)
	v_pk_mul_f32 v[32:33], v[22:23], v[28:29] op_sel_hi:[1,0]
	v_pk_mul_f32 v[34:35], v[20:21], v[28:29] op_sel_hi:[1,0]
	s_waitcnt vmcnt(0)
	v_pk_mul_f32 v[30:31], v[26:27], v[36:37] op_sel_hi:[1,0]
	v_pk_mul_f32 v[28:29], v[24:25], v[36:37] op_sel_hi:[1,0]
	s_cbranch_execnz .LBB0_768

.LBB0_768:
	v_add_u32_e32 v20, v3, v87
	ds_write2_b32 v20, v34, v35 offset1:1
	ds_write2_b32 v20, v32, v33 offset0:2 offset1:3
	v_add_u32_e32 v21, 0x420, v20
	v_add_u32_e32 v20, 0x428, v20
	s_and_b64 vcc, exec, s[6:7]
	ds_write2_b32 v21, v28, v29 offset1:1
	ds_write2_b32 v20, v30, v31 offset1:1
	s_cbranch_vccnz .LBB0_836
	global_load_dword v20, v79, s[14:15] offset:128 nt
	global_load_dword v28, v79, s[14:15] offset:160 nt
	s_waitcnt vmcnt(1)
	v_pk_mul_f32 v[24:25], v[14:15], v[20:21] op_sel_hi:[1,0]
	v_pk_mul_f32 v[26:27], v[12:13], v[20:21] op_sel_hi:[1,0]
	s_waitcnt vmcnt(0)
	v_pk_mul_f32 v[22:23], v[18:19], v[28:29] op_sel_hi:[1,0]
	v_pk_mul_f32 v[20:21], v[16:17], v[28:29] op_sel_hi:[1,0]
	s_cbranch_execnz .LBB0_771

.LBB0_771:
	v_add_u32_e32 v28, v3, v89
	v_add_u32_e32 v12, 0x420, v28
	ds_write2_b32 v12, v26, v27 offset1:1
	v_add_u32_e32 v12, 0x428, v28
	ds_write2_b32 v12, v24, v25 offset1:1
	v_add_u32_e32 v12, 0x840, v28
	ds_write2_b32 v12, v20, v21 offset1:1
	v_add_u32_e32 v12, 0x848, v28
	s_and_b64 vcc, exec, s[6:7]
	ds_write2_b32 v12, v22, v23 offset1:1
	s_cbranch_vccnz .LBB0_837
	global_load_dword v12, v79, s[14:15] offset:192 nt
	global_load_dword v20, v79, s[14:15] offset:224 nt
	s_waitcnt vmcnt(1)
	v_pk_mul_f32 v[16:17], v[6:7], v[12:13] op_sel_hi:[1,0]
	v_pk_mul_f32 v[18:19], v[4:5], v[12:13] op_sel_hi:[1,0]
	s_waitcnt vmcnt(0)
	v_pk_mul_f32 v[14:15], v[10:11], v[20:21] op_sel_hi:[1,0]
	v_pk_mul_f32 v[12:13], v[8:9], v[20:21] op_sel_hi:[1,0]
	s_cbranch_execnz .LBB0_774

.LBB0_776:
	s_andn2_b64 vcc, exec, s[6:7]
	s_cbranch_vccnz .LBB0_790
	s_add_i32 s6, s51, 0xef80
	s_and_b32 s7, s6, 0xffff
	s_mul_i32 s7, s7, 0xba2f
	s_lshr_b32 s18, s7, 16
	s_lshr_b32 s7, s7, 22
	s_mulk_i32 s7, 0x58
	s_sub_i32 s6, s6, s7
	s_and_b32 s27, s6, 0xffff
	s_and_b32 s26, s18, 0xffc0
	v_or_b32_e32 v36, s26, v0
	s_lshl_b32 s90, s27, 7
	v_lshl_add_u64 v[4:5], v[70:71], 0, s[90:91]
	v_mul_u32_u24_e32 v180, 0x2c00, v36
	v_mad_u64_u32 v[6:7], s[6:7], v36, s66, v[4:5]
	v_lshl_add_u64 v[4:5], v[4:5], 0, v[180:181]
	s_mov_b32 s0, 0x16000
	v_add_co_u32_e32 v8, vcc, s0, v4
	s_mov_b32 s0, 0x2c000
	s_nop 0
	v_addc_co_u32_e32 v9, vcc, 0, v5, vcc
	global_load_dwordx4 v[28:31], v[6:7], off nt
	global_load_dwordx4 v[32:35], v[8:9], off nt
	v_add_co_u32_e32 v6, vcc, s0, v4
	s_mov_b32 s0, 0x42000
	s_nop 0
	v_addc_co_u32_e32 v7, vcc, 0, v5, vcc
	v_add_co_u32_e32 v8, vcc, s0, v4
	s_mov_b32 s0, 0x58000
	s_nop 0
	v_addc_co_u32_e32 v9, vcc, 0, v5, vcc
	global_load_dwordx4 v[20:23], v[6:7], off nt
	global_load_dwordx4 v[24:27], v[8:9], off nt
	v_add_co_u32_e32 v6, vcc, s0, v4
	v_readlane_b32 s18, v251, 20
	s_nop 0
	v_addc_co_u32_e32 v7, vcc, 0, v5, vcc
	v_add_co_u32_e32 v8, vcc, 0x6e000, v4
	v_readlane_b32 s19, v251, 21
	s_nop 0
	v_addc_co_u32_e32 v9, vcc, 0, v5, vcc
	global_load_dwordx4 v[12:15], v[6:7], off nt
	global_load_dwordx4 v[16:19], v[8:9], off nt
	v_add_co_u32_e32 v6, vcc, 0x84000, v4
	v_cndmask_b32_e64 v37, 0, 1, s[18:19]
	s_nop 0
	v_addc_co_u32_e32 v7, vcc, 0, v5, vcc
	v_add_co_u32_e32 v8, vcc, 0x9a000, v4
	v_cmp_ne_u32_e64 s[6:7], 1, v37
	s_nop 0
	v_addc_co_u32_e32 v9, vcc, 0, v5, vcc
	global_load_dwordx4 v[4:7], v[6:7], off nt
	s_nop 0
	global_load_dwordx4 v[8:11], v[8:9], off nt
	s_andn2_b64 vcc, exec, s[18:19]
	v_add_lshl_u32 v79, v0, s26, 2
	s_cbranch_vccnz .LBB0_830
	v_lshlrev_b32_e32 v36, 2, v36
	global_load_dword v36, v36, s[14:15] nt
	s_nop 0
	global_load_dword v92, v79, s[14:15] offset:32 nt
	s_waitcnt vmcnt(0)
	v_pk_mul_f32 v[80:81], v[30:31], v[36:37] op_sel_hi:[1,0]
	v_pk_mul_f32 v[82:83], v[28:29], v[36:37] op_sel_hi:[1,0]
	v_pk_mul_f32 v[38:39], v[34:35], v[92:93] op_sel_hi:[1,0]
	v_pk_mul_f32 v[36:37], v[32:33], v[92:93] op_sel_hi:[1,0]
	s_cbranch_execnz .LBB0_780

.LBB0_791:
	s_andn2_b64 vcc, exec, s[6:7]
	s_cbranch_vccnz .LBB0_793
	s_add_i32 s6, s49, 0x24600
	s_and_b32 s7, s6, 0x1ffc0
	s_lshl_b32 s6, s51, 5
	s_and_b32 s6, s6, 0x3e0
	v_or_b32_e32 v6, s7, v0
	s_lshl_b32 s90, s6, 2
	v_lshl_add_u64 v[4:5], v[72:73], 0, s[90:91]
	v_lshlrev_b32_e32 v180, 12, v6
	v_lshl_add_u64 v[32:33], v[4:5], 0, v[180:181]
	v_add_co_u32_e32 v8, vcc, 0x8000, v32
	global_load_dwordx4 v[4:7], v[32:33], off nt
	s_nop 0
	v_addc_co_u32_e32 v9, vcc, 0, v33, vcc
	s_mov_b32 s0, 0x10000
	global_load_dwordx4 v[8:11], v[8:9], off nt
	v_add_co_u32_e32 v12, vcc, s0, v32
	s_mov_b32 s0, 0x18000
	s_nop 0
	v_addc_co_u32_e32 v13, vcc, 0, v33, vcc
	global_load_dwordx4 v[12:15], v[12:13], off nt
	s_waitcnt vmcnt(0)
	v_add_co_u32_e32 v16, vcc, s0, v32
	v_add_u32_e32 v36, v3, v84
	s_nop 0
	v_addc_co_u32_e32 v17, vcc, 0, v33, vcc
	global_load_dwordx4 v[16:19], v[16:17], off nt
	v_add_co_u32_e32 v20, vcc, 0x20000, v32
	s_lshl_b32 s90, s7, 1
	s_nop 0
	v_addc_co_u32_e32 v21, vcc, 0, v33, vcc
	global_load_dwordx4 v[20:23], v[20:21], off nt
	v_add_co_u32_e32 v24, vcc, 0x28000, v32
	s_nop 1
	v_addc_co_u32_e32 v25, vcc, 0, v33, vcc
	global_load_dwordx4 v[24:27], v[24:25], off nt
	v_add_co_u32_e32 v28, vcc, 0x30000, v32
	s_nop 1
	v_addc_co_u32_e32 v29, vcc, 0, v33, vcc
	global_load_dwordx4 v[28:31], v[28:29], off nt
	v_add_co_u32_e32 v32, vcc, 0x38000, v32
	s_nop 1
	v_addc_co_u32_e32 v33, vcc, 0, v33, vcc
	global_load_dwordx4 v[32:35], v[32:33], off nt
	ds_write2_b32 v36, v4, v5 offset1:1
	ds_write2_b32 v36, v6, v7 offset0:2 offset1:3
	v_add_u32_e32 v4, 0x420, v36
	ds_write2_b32 v4, v8, v9 offset1:1
	v_add_u32_e32 v4, 0x428, v36
	ds_write2_b32 v4, v10, v11 offset1:1
	v_add_u32_e32 v4, 0x840, v36
	ds_write2_b32 v4, v12, v13 offset1:1
	v_add_u32_e32 v4, 0x848, v36
	ds_write2_b32 v4, v14, v15 offset1:1
	v_add_u32_e32 v4, 0xc60, v36
	s_waitcnt vmcnt(4)
	ds_write2_b32 v4, v16, v17 offset1:1
	v_add_u32_e32 v4, 0xc68, v36
	ds_write2_b32 v4, v18, v19 offset1:1
	v_add_u32_e32 v4, 0x1080, v36
	s_waitcnt vmcnt(3)
	ds_write2_b32 v4, v20, v21 offset1:1
	v_add_u32_e32 v4, 0x1088, v36
	ds_write2_b32 v4, v22, v23 offset1:1
	v_add_u32_e32 v4, 0x14a0, v36
	s_waitcnt vmcnt(2)
	ds_write2_b32 v4, v24, v25 offset1:1
	v_add_u32_e32 v4, 0x14a8, v36
	ds_write2_b32 v4, v26, v27 offset1:1
	v_add_u32_e32 v4, 0x18c0, v36
	s_waitcnt vmcnt(1)
	ds_write2_b32 v4, v28, v29 offset1:1
	v_add_u32_e32 v4, 0x18c8, v36
	ds_write2_b32 v4, v30, v31 offset1:1
	v_add_u32_e32 v4, 0x1ce0, v36
	s_waitcnt vmcnt(0)
	ds_write2_b32 v4, v32, v33 offset1:1
	v_add_u32_e32 v4, 0x1ce8, v36
	ds_write2_b32 v4, v34, v35 offset1:1
	s_waitcnt lgkmcnt(0)
	ds_read2_b32 v[10:11], v90 offset0:33 offset1:41
	ds_read2_b32 v[12:13], v90 offset1:8
	ds_read2_b32 v[14:15], v90 offset0:66 offset1:74
	ds_read2_b32 v[16:17], v90 offset0:99 offset1:107
	ds_read2_b32 v[18:19], v90 offset0:132 offset1:140
	ds_read2_b32 v[20:21], v90 offset0:165 offset1:173
	ds_read2_b32 v[22:23], v90 offset0:198 offset1:206
	ds_read2_b32 v[24:25], v90 offset0:231 offset1:239
	v_lshl_add_u64 v[4:5], v[54:55], 0, s[90:91]
	s_waitcnt lgkmcnt(6)
	v_cvt_pk_bf16_f32 v6, v12, v10
	v_or_b32_e32 v10, s6, v0
	v_mul_u32_u24_e32 v180, 0x1600, v10
	v_or_b32_e32 v10, s6, v85
	s_waitcnt lgkmcnt(4)
	v_cvt_pk_bf16_f32 v7, v14, v16
	s_waitcnt lgkmcnt(2)
	v_cvt_pk_bf16_f32 v8, v18, v20
	s_waitcnt lgkmcnt(0)
	v_cvt_pk_bf16_f32 v9, v22, v24
	v_lshl_add_u64 v[26:27], v[4:5], 0, v[180:181]
	v_mul_u32_u24_e32 v180, 0x1600, v10
	global_store_dwordx4 v[26:27], v[6:9], off
	s_nop 1
	v_cvt_pk_bf16_f32 v6, v13, v11
	v_cvt_pk_bf16_f32 v7, v15, v17
	v_cvt_pk_bf16_f32 v8, v19, v21
	v_cvt_pk_bf16_f32 v9, v23, v25
	v_lshl_add_u64 v[10:11], v[4:5], 0, v[180:181]
	global_store_dwordx4 v[10:11], v[6:9], off
	ds_read2_b32 v[10:11], v90 offset0:16 offset1:24
	ds_read2_b32 v[12:13], v90 offset0:49 offset1:57
	ds_read2_b32 v[14:15], v90 offset0:82 offset1:90
	ds_read2_b32 v[16:17], v90 offset0:115 offset1:123
	ds_read2_b32 v[18:19], v90 offset0:148 offset1:156
	ds_read2_b32 v[20:21], v90 offset0:181 offset1:189
	ds_read2_b32 v[22:23], v90 offset0:214 offset1:222
	ds_read2_b32 v[24:25], v90 offset0:247 offset1:255
	s_waitcnt lgkmcnt(6)
	v_cvt_pk_bf16_f32 v6, v10, v12
	v_or_b32_e32 v10, s6, v86
	v_mul_u32_u24_e32 v180, 0x1600, v10
	v_or_b32_e32 v10, s6, v88
	s_waitcnt lgkmcnt(4)
	v_cvt_pk_bf16_f32 v7, v14, v16
	s_waitcnt lgkmcnt(2)
	v_cvt_pk_bf16_f32 v8, v18, v20
	s_waitcnt lgkmcnt(0)
	v_cvt_pk_bf16_f32 v9, v22, v24
	v_lshl_add_u64 v[26:27], v[4:5], 0, v[180:181]
	v_mul_u32_u24_e32 v180, 0x1600, v10
	global_store_dwordx4 v[26:27], v[6:9], off
	v_lshl_add_u64 v[4:5], v[4:5], 0, v[180:181]
	s_nop 0
	v_cvt_pk_bf16_f32 v6, v11, v13
	v_cvt_pk_bf16_f32 v7, v15, v17
	v_cvt_pk_bf16_f32 v8, v19, v21
	v_cvt_pk_bf16_f32 v9, v23, v25
	global_store_dwordx4 v[4:5], v[6:9], off
	s_waitcnt lgkmcnt(0)

.LBB0_794:
	s_andn2_b64 vcc, exec, s[6:7]
	s_cbranch_vccnz .LBB0_808
	s_add_i32 s6, s51, 0xfa80
	s_and_b32 s7, s6, 0xffff
	s_mul_i32 s7, s7, 0xba2f
	s_lshr_b32 s18, s7, 16
	s_lshr_b32 s7, s7, 22
	s_mulk_i32 s7, 0x58
	s_sub_i32 s6, s6, s7
	s_and_b32 s27, s6, 0xffff
	s_and_b32 s26, s18, 0xffc0
	v_or_b32_e32 v36, s26, v0
	s_lshl_b32 s90, s27, 7
	v_lshl_add_u64 v[4:5], v[74:75], 0, s[90:91]
	v_mul_u32_u24_e32 v180, 0x2c00, v36
	v_mad_u64_u32 v[6:7], s[6:7], v36, s66, v[4:5]
	v_lshl_add_u64 v[4:5], v[4:5], 0, v[180:181]
	s_mov_b32 s0, 0x16000
	v_add_co_u32_e32 v8, vcc, s0, v4
	s_mov_b32 s0, 0x2c000
	s_nop 0
	v_addc_co_u32_e32 v9, vcc, 0, v5, vcc
	global_load_dwordx4 v[28:31], v[6:7], off nt
	global_load_dwordx4 v[32:35], v[8:9], off nt
	v_add_co_u32_e32 v6, vcc, s0, v4
	s_mov_b32 s0, 0x42000
	s_nop 0
	v_addc_co_u32_e32 v7, vcc, 0, v5, vcc
	v_add_co_u32_e32 v8, vcc, s0, v4
	s_mov_b32 s0, 0x58000
	s_nop 0
	v_addc_co_u32_e32 v9, vcc, 0, v5, vcc
	global_load_dwordx4 v[20:23], v[6:7], off nt
	global_load_dwordx4 v[24:27], v[8:9], off nt
	v_add_co_u32_e32 v6, vcc, s0, v4
	v_cndmask_b32_e64 v37, 0, 1, s[30:31]
	s_nop 0
	v_addc_co_u32_e32 v7, vcc, 0, v5, vcc
	v_add_co_u32_e32 v8, vcc, 0x6e000, v4
	v_cmp_ne_u32_e64 s[6:7], 1, v37
	s_nop 0
	v_addc_co_u32_e32 v9, vcc, 0, v5, vcc
	global_load_dwordx4 v[12:15], v[6:7], off nt
	global_load_dwordx4 v[16:19], v[8:9], off nt
	v_add_co_u32_e32 v6, vcc, 0x84000, v4
	v_add_lshl_u32 v79, v0, s26, 2
	s_nop 0
	v_addc_co_u32_e32 v7, vcc, 0, v5, vcc
	v_add_co_u32_e32 v8, vcc, 0x9a000, v4
	s_nop 1
	v_addc_co_u32_e32 v9, vcc, 0, v5, vcc
	global_load_dwordx4 v[4:7], v[6:7], off nt
	s_nop 0
	global_load_dwordx4 v[8:11], v[8:9], off nt
	s_andn2_b64 vcc, exec, s[30:31]
	s_cbranch_vccnz .LBB0_826
	v_lshlrev_b32_e32 v36, 2, v36
	global_load_dword v36, v36, s[16:17] nt
	s_nop 0
	global_load_dword v92, v79, s[16:17] offset:32 nt
	s_waitcnt vmcnt(0)
	v_pk_mul_f32 v[80:81], v[30:31], v[36:37] op_sel_hi:[1,0]
	v_pk_mul_f32 v[82:83], v[28:29], v[36:37] op_sel_hi:[1,0]
	v_pk_mul_f32 v[38:39], v[34:35], v[92:93] op_sel_hi:[1,0]
	v_pk_mul_f32 v[36:37], v[32:33], v[92:93] op_sel_hi:[1,0]
	s_cbranch_execnz .LBB0_798

.LBB0_798:
	s_waitcnt vmcnt(0)
	v_add_u32_e32 v28, v3, v84
	ds_write2_b32 v28, v82, v83 offset1:1
	ds_write2_b32 v28, v80, v81 offset0:2 offset1:3
	v_add_u32_e32 v29, 0x420, v28
	v_add_u32_e32 v28, 0x428, v28
	s_and_b64 vcc, exec, s[6:7]
	ds_write2_b32 v29, v36, v37 offset1:1
	ds_write2_b32 v28, v38, v39 offset1:1
	s_cbranch_vccnz .LBB0_827
	global_load_dword v28, v79, s[16:17] offset:64 nt
	global_load_dword v36, v79, s[16:17] offset:96 nt
	s_waitcnt vmcnt(1)
	v_pk_mul_f32 v[32:33], v[22:23], v[28:29] op_sel_hi:[1,0]
	v_pk_mul_f32 v[34:35], v[20:21], v[28:29] op_sel_hi:[1,0]
	s_waitcnt vmcnt(0)
	v_pk_mul_f32 v[30:31], v[26:27], v[36:37] op_sel_hi:[1,0]
	v_pk_mul_f32 v[28:29], v[24:25], v[36:37] op_sel_hi:[1,0]
	s_cbranch_execnz .LBB0_801

.LBB0_801:
	v_add_u32_e32 v20, v3, v87
	ds_write2_b32 v20, v34, v35 offset1:1
	ds_write2_b32 v20, v32, v33 offset0:2 offset1:3
	v_add_u32_e32 v21, 0x420, v20
	v_add_u32_e32 v20, 0x428, v20
	s_and_b64 vcc, exec, s[6:7]
	ds_write2_b32 v21, v28, v29 offset1:1
	ds_write2_b32 v20, v30, v31 offset1:1
	s_cbranch_vccnz .LBB0_828
	global_load_dword v20, v79, s[16:17] offset:128 nt
	global_load_dword v28, v79, s[16:17] offset:160 nt
	s_waitcnt vmcnt(1)
	v_pk_mul_f32 v[24:25], v[14:15], v[20:21] op_sel_hi:[1,0]
	v_pk_mul_f32 v[26:27], v[12:13], v[20:21] op_sel_hi:[1,0]
	s_waitcnt vmcnt(0)
	v_pk_mul_f32 v[22:23], v[18:19], v[28:29] op_sel_hi:[1,0]
	v_pk_mul_f32 v[20:21], v[16:17], v[28:29] op_sel_hi:[1,0]
	s_cbranch_execnz .LBB0_804

.LBB0_804:
	v_add_u32_e32 v28, v3, v89
	v_add_u32_e32 v12, 0x420, v28
	ds_write2_b32 v12, v26, v27 offset1:1
	v_add_u32_e32 v12, 0x428, v28
	ds_write2_b32 v12, v24, v25 offset1:1
	v_add_u32_e32 v12, 0x840, v28
	ds_write2_b32 v12, v20, v21 offset1:1
	v_add_u32_e32 v12, 0x848, v28
	s_and_b64 vcc, exec, s[6:7]
	ds_write2_b32 v12, v22, v23 offset1:1
	s_cbranch_vccnz .LBB0_829
	global_load_dword v12, v79, s[16:17] offset:192 nt
	global_load_dword v20, v79, s[16:17] offset:224 nt
	s_waitcnt vmcnt(1)
	v_pk_mul_f32 v[16:17], v[6:7], v[12:13] op_sel_hi:[1,0]
	v_pk_mul_f32 v[18:19], v[4:5], v[12:13] op_sel_hi:[1,0]
	s_waitcnt vmcnt(0)
	v_pk_mul_f32 v[14:15], v[10:11], v[20:21] op_sel_hi:[1,0]
	v_pk_mul_f32 v[12:13], v[8:9], v[20:21] op_sel_hi:[1,0]
	s_cbranch_execnz .LBB0_807

.LBB0_809:
	s_andn2_b64 vcc, exec, s[6:7]
	s_cbranch_vccnz .LBB0_698
	s_mul_hi_i32 s6, s51, 0x2e8ba2e9
	s_lshr_b32 s7, s6, 31
	s_ashr_i32 s52, s6, 4
	s_add_i32 s52, s52, s7
	s_mul_i32 s6, s52, 0xfffff500
	s_add_i32 s26, s45, s6
	s_lshl_b32 s18, s52, 6
	v_or_b32_e32 v36, s18, v0
	s_ashr_i32 s27, s26, 31
	v_lshl_add_u64 v[4:5], s[26:27], 2, v[76:77]
	v_or_b32_e32 v8, 8, v36
	v_mad_i64_i32 v[6:7], s[6:7], v36, s66, v[4:5]
	v_mad_i64_i32 v[8:9], s[6:7], v8, s66, v[4:5]
	global_load_dwordx4 v[28:31], v[6:7], off nt
	global_load_dwordx4 v[32:35], v[8:9], off nt
	v_or_b32_e32 v6, 16, v36
	v_or_b32_e32 v8, 24, v36
	v_mad_i64_i32 v[6:7], s[6:7], v6, s66, v[4:5]
	v_mad_i64_i32 v[8:9], s[6:7], v8, s66, v[4:5]
	global_load_dwordx4 v[20:23], v[6:7], off nt
	global_load_dwordx4 v[24:27], v[8:9], off nt
	v_or_b32_e32 v6, 32, v36
	v_or_b32_e32 v8, 40, v36
	v_mad_i64_i32 v[6:7], s[6:7], v6, s66, v[4:5]
	v_mad_i64_i32 v[8:9], s[6:7], v8, s66, v[4:5]
	global_load_dwordx4 v[12:15], v[6:7], off nt
	global_load_dwordx4 v[16:19], v[8:9], off nt
	v_or_b32_e32 v6, 48, v36
	v_or_b32_e32 v8, 56, v36
	v_mad_i64_i32 v[6:7], s[6:7], v6, s66, v[4:5]
	v_mad_i64_i32 v[8:9], s[6:7], v8, s66, v[4:5]
	global_load_dwordx4 v[4:7], v[6:7], off nt
	s_nop 0
	global_load_dwordx4 v[8:11], v[8:9], off nt
	v_cndmask_b32_e64 v37, 0, 1, s[30:31]
	v_cmp_ne_u32_e64 s[6:7], 1, v37
	s_andn2_b64 vcc, exec, s[30:31]
	s_cbranch_vccnz .LBB0_821
	s_ashr_i32 s19, s18, 31
	v_ashrrev_i32_e32 v37, 31, v36
	v_lshl_add_u64 v[38:39], s[18:19], 0, v[0:1]
	v_lshl_add_u64 v[36:37], v[36:37], 2, s[16:17]
	v_lshl_add_u64 v[38:39], v[38:39], 2, s[16:17]
	global_load_dword v36, v[36:37], off nt
	s_nop 0
	global_load_dword v92, v[38:39], off offset:32 nt
	s_waitcnt vmcnt(0)
	v_pk_mul_f32 v[80:81], v[30:31], v[36:37] op_sel_hi:[1,0]
	v_pk_mul_f32 v[82:83], v[28:29], v[36:37] op_sel_hi:[1,0]
	v_pk_mul_f32 v[38:39], v[34:35], v[92:93] op_sel_hi:[1,0]
	v_pk_mul_f32 v[36:37], v[32:33], v[92:93] op_sel_hi:[1,0]
	s_cbranch_execnz .LBB0_813

.LBB0_813:
	s_waitcnt vmcnt(0)
	v_add_u32_e32 v28, v3, v84
	ds_write2_b32 v28, v82, v83 offset1:1
	ds_write2_b32 v28, v80, v81 offset0:2 offset1:3
	v_add_u32_e32 v29, 0x420, v28
	v_add_u32_e32 v28, 0x428, v28
	s_and_b64 vcc, exec, s[6:7]
	ds_write2_b32 v29, v36, v37 offset1:1
	ds_write2_b32 v28, v38, v39 offset1:1
	s_cbranch_vccnz .LBB0_822
	s_ashr_i32 s19, s18, 31
	v_lshl_add_u64 v[28:29], s[18:19], 0, v[0:1]
	v_lshl_add_u64 v[28:29], v[28:29], 2, s[16:17]
	global_load_dword v30, v[28:29], off offset:64 nt
	s_nop 0
	global_load_dword v28, v[28:29], off offset:96 nt
	s_waitcnt vmcnt(1)
	v_pk_mul_f32 v[32:33], v[22:23], v[30:31] op_sel_hi:[1,0]
	v_pk_mul_f32 v[34:35], v[20:21], v[30:31] op_sel_hi:[1,0]
	s_waitcnt vmcnt(0)
	v_pk_mul_f32 v[30:31], v[26:27], v[28:29] op_sel_hi:[1,0]
	v_pk_mul_f32 v[28:29], v[24:25], v[28:29] op_sel_hi:[1,0]
	s_cbranch_execnz .LBB0_816

.LBB0_816:
	v_add_u32_e32 v20, v3, v87
	ds_write2_b32 v20, v34, v35 offset1:1
	ds_write2_b32 v20, v32, v33 offset0:2 offset1:3
	v_add_u32_e32 v21, 0x420, v20
	v_add_u32_e32 v20, 0x428, v20
	s_and_b64 vcc, exec, s[6:7]
	ds_write2_b32 v21, v28, v29 offset1:1
	ds_write2_b32 v20, v30, v31 offset1:1
	s_cbranch_vccnz .LBB0_823
	s_ashr_i32 s19, s18, 31
	v_lshl_add_u64 v[20:21], s[18:19], 0, v[0:1]
	v_lshl_add_u64 v[20:21], v[20:21], 2, s[16:17]
	global_load_dword v22, v[20:21], off offset:128 nt
	s_nop 0
	global_load_dword v20, v[20:21], off offset:160 nt
	s_waitcnt vmcnt(1)
	v_pk_mul_f32 v[24:25], v[14:15], v[22:23] op_sel_hi:[1,0]
	v_pk_mul_f32 v[26:27], v[12:13], v[22:23] op_sel_hi:[1,0]
	s_waitcnt vmcnt(0)
	v_pk_mul_f32 v[22:23], v[18:19], v[20:21] op_sel_hi:[1,0]
	v_pk_mul_f32 v[20:21], v[16:17], v[20:21] op_sel_hi:[1,0]
	s_cbranch_execnz .LBB0_819

.LBB0_819:
	v_add_u32_e32 v28, v3, v89
	v_add_u32_e32 v12, 0x420, v28
	ds_write2_b32 v12, v26, v27 offset1:1
	v_add_u32_e32 v12, 0x428, v28
	ds_write2_b32 v12, v24, v25 offset1:1
	v_add_u32_e32 v12, 0x840, v28
	ds_write2_b32 v12, v20, v21 offset1:1
	v_add_u32_e32 v12, 0x848, v28
	s_and_b64 vcc, exec, s[6:7]
	ds_write2_b32 v12, v22, v23 offset1:1
	s_cbranch_vccnz .LBB0_824
	s_ashr_i32 s19, s18, 31
	v_lshl_add_u64 v[12:13], s[18:19], 0, v[0:1]
	v_lshl_add_u64 v[12:13], v[12:13], 2, s[16:17]
	global_load_dword v14, v[12:13], off offset:192 nt
	s_nop 0
	global_load_dword v12, v[12:13], off offset:224 nt
	s_waitcnt vmcnt(1)
	v_pk_mul_f32 v[16:17], v[6:7], v[14:15] op_sel_hi:[1,0]
	v_pk_mul_f32 v[18:19], v[4:5], v[14:15] op_sel_hi:[1,0]
	s_waitcnt vmcnt(0)
	v_pk_mul_f32 v[14:15], v[10:11], v[12:13] op_sel_hi:[1,0]
	v_pk_mul_f32 v[12:13], v[8:9], v[12:13] op_sel_hi:[1,0]
	s_cbranch_execnz .LBB0_697
	s_branch .LBB0_825

.LBB0_855:
	s_add_i32 s14, s25, 0xffffc000
	s_cmpk_lt_i32 s25, 0x4000
	s_cselect_b64 s[12:13], -1, 0
	s_and_b64 s[10:11], s[12:13], exec
	v_readlane_b32 s68, v251, 22
	s_cselect_b32 s10, s25, s14
	v_readlane_b32 s69, v251, 23
	v_readlane_b32 s70, v251, 24
	v_readlane_b32 s71, v251, 25
	s_cselect_b32 s16, s69, s71
	s_cselect_b32 s17, s68, s70
	s_ashr_i32 s11, s10, 31
	s_lshl_b64 s[14:15], s[10:11], 12
	s_add_u32 s14, s17, s14
	s_addc_u32 s15, s16, s15
	v_lshlrev_b32_e32 v39, 4, v188
	global_load_dwordx4 v[32:35], v39, s[14:15] nt
	global_load_dwordx4 v[28:31], v39, s[14:15] offset:1024 nt
	global_load_dwordx4 v[24:27], v39, s[14:15] offset:2048 nt
	s_waitcnt lgkmcnt(0)
	global_load_dwordx4 v[20:23], v39, s[14:15] offset:3072 nt
	s_add_i32 s18, s25, s96
	s_cmpk_lt_i32 s18, 0x4800
	s_cselect_b64 s[14:15], -1, 0
	s_cmpk_gt_i32 s18, 0x47ff
	v_readlane_b32 s72, v251, 26
	v_readlane_b32 s73, v251, 27
	v_readlane_b32 s74, v251, 28
	v_readlane_b32 s75, v251, 29
	v_readlane_b32 s76, v251, 30
	v_readlane_b32 s77, v251, 31
	v_readlane_b32 s78, v251, 32
	v_readlane_b32 s79, v251, 33
	v_readlane_b32 s80, v251, 34
	v_readlane_b32 s81, v251, 35
	v_readlane_b32 s82, v251, 36
	v_readlane_b32 s83, v251, 37
	s_cbranch_scc1 .LBB0_857
	s_add_i32 s16, s18, 0xffffc000
	s_cmpk_lt_i32 s18, 0x4000
	v_readlane_b32 s68, v251, 22
	s_cselect_b32 s16, s18, s16
	v_readlane_b32 s69, v251, 23
	v_readlane_b32 s70, v251, 24
	v_readlane_b32 s71, v251, 25
	s_cselect_b32 s19, s69, s71
	s_cselect_b32 s25, s68, s70
	s_ashr_i32 s17, s16, 31
	s_lshl_b64 s[16:17], s[16:17], 12
	s_add_u32 s16, s25, s16
	s_addc_u32 s17, s19, s17
	global_load_dwordx4 v[16:19], v39, s[16:17] nt
	global_load_dwordx4 v[12:15], v39, s[16:17] offset:1024 nt
	global_load_dwordx4 v[8:11], v39, s[16:17] offset:2048 nt
	global_load_dwordx4 v[4:7], v39, s[16:17] offset:3072 nt
	v_readlane_b32 s72, v251, 26
	v_readlane_b32 s73, v251, 27
	v_readlane_b32 s74, v251, 28
	v_readlane_b32 s75, v251, 29
	v_readlane_b32 s76, v251, 30
	v_readlane_b32 s77, v251, 31
	v_readlane_b32 s78, v251, 32
	v_readlane_b32 s79, v251, 33
	v_readlane_b32 s80, v251, 34
	v_readlane_b32 s81, v251, 35
	v_readlane_b32 s82, v251, 36
	v_readlane_b32 s83, v251, 37

.LBB0_865:
	v_bfe_u32 v1, v0, 9, 4
	v_cmp_gt_u32_e32 vcc, 8, v1
	v_mov_b32_e32 v6, 0
	s_and_saveexec_b64 s[10:11], vcc
	s_cbranch_execz .LBB0_864
	v_readlane_b32 s68, v251, 22
	v_and_b32_e32 v8, 0x3fe, v3
	v_ashrrev_i32_e32 v10, 13, v0
	v_readlane_b32 s82, v251, 36
	v_readlane_b32 s83, v251, 37
	v_lshl_or_b32 v6, v10, 10, v8
	v_mul_u32_u24_e32 v11, 0xe08, v8
	v_mov_b64_e32 v[8:9], s[82:83]
	s_mov_b32 s12, 0xe08000
	v_mad_i64_i32 v[8:9], s[12:13], v10, s12, v[8:9]
	v_lshlrev_b32_e32 v180, 2, v11
	v_lshl_add_u64 v[8:9], v[8:9], 0, v[180:181]
	v_lshlrev_b32_e32 v180, 2, v1
	v_lshl_add_u64 v[8:9], v[8:9], 0, v[180:181]
	v_add_co_u32_e32 v10, vcc, 0x3000, v8
	v_ashrrev_i32_e32 v7, 31, v6
	v_readlane_b32 s80, v251, 34
	v_readlane_b32 s81, v251, 35
	v_addc_co_u32_e32 v11, vcc, 0, v9, vcc
	s_nop 0
	v_lshl_add_u64 v[6:7], v[6:7], 2, s[80:81]
	v_add_co_u32_e32 v8, vcc, 0x7000, v8
	global_load_dwordx2 v[6:7], v[6:7], off nt
	s_nop 0
	v_addc_co_u32_e32 v9, vcc, 0, v9, vcc
	global_load_dword v10, v[10:11], off offset:2048 nt
	s_nop 0
	global_load_dword v11, v[8:9], off offset:32 nt
	v_readlane_b32 s69, v251, 23
	v_readlane_b32 s70, v251, 24
	v_readlane_b32 s71, v251, 25
	v_readlane_b32 s72, v251, 26
	v_readlane_b32 s73, v251, 27
	v_readlane_b32 s74, v251, 28
	v_readlane_b32 s75, v251, 29
	v_readlane_b32 s76, v251, 30
	v_readlane_b32 s77, v251, 31
	v_readlane_b32 s78, v251, 32
	v_readlane_b32 s79, v251, 33
	s_waitcnt vmcnt(0)
	v_pk_mul_f32 v[6:7], v[6:7], v[10:11]
	s_nop 0
	v_cvt_pk_bf16_f32 v6, v6, v7
	s_branch .LBB0_864
